# plus GLA prefix-scan loops: 8 LDS reads batched per iteration, counted lgkmcnt
# speedup vs baseline: 1.0343x; 1.0066x over previous
.LBB0_97:
	v_add_u32_e32 v61, s6, v58
	v_add_u32_e32 v60, -7, v57
	v_add_u32_e32 v62, 31, v61
	v_cndmask_b32_e32 v60, v62, v60, vcc
	v_lshl_add_u32 v140, v60, 9, v56
	v_add_u32_e32 v60, -6, v57
	v_add_u32_e32 v62, 30, v61
	v_cndmask_b32_e32 v60, v62, v60, vcc
	v_lshl_add_u32 v141, v60, 9, v56
	v_add_u32_e32 v60, -5, v57
	v_add_u32_e32 v62, 29, v61
	v_cndmask_b32_e32 v60, v62, v60, vcc
	v_lshl_add_u32 v142, v60, 9, v56
	v_add_u32_e32 v60, -4, v57
	v_add_u32_e32 v62, 28, v61
	v_cndmask_b32_e32 v60, v62, v60, vcc
	v_lshl_add_u32 v143, v60, 9, v56
	v_add_u32_e32 v60, -3, v57
	v_add_u32_e32 v62, 27, v61
	v_cndmask_b32_e32 v60, v62, v60, vcc
	v_lshl_add_u32 v144, v60, 9, v56
	v_add_u32_e32 v60, -2, v57
	v_add_u32_e32 v62, 26, v61
	v_cndmask_b32_e32 v60, v62, v60, vcc
	v_lshl_add_u32 v145, v60, 9, v56
	v_add_u32_e32 v60, -1, v57
	v_add_u32_e32 v62, 25, v61
	v_cndmask_b32_e32 v60, v62, v60, vcc
	v_lshl_add_u32 v146, v60, 9, v56
	v_add_u32_e32 v60, 24, v61
	v_cndmask_b32_e32 v60, v60, v57, vcc
	v_lshl_add_u32 v147, v60, 9, v56
	ds_read_b32 v148, v140
	ds_read_b32 v149, v141
	ds_read_b32 v150, v142
	ds_read_b32 v151, v143
	ds_read_b32 v152, v144
	ds_read_b32 v153, v145
	ds_read_b32 v154, v146
	ds_read_b32 v155, v147
	s_add_i32 s6, s6, -8
	s_cmp_eq_u32 s6, 0
	v_add_u32_e32 v57, 8, v57
	s_waitcnt lgkmcnt(7)
	v_add_f32_e32 v59, v59, v148
	ds_write_b32 v140, v59
	s_waitcnt lgkmcnt(7)
	v_add_f32_e32 v59, v59, v149
	ds_write_b32 v141, v59
	s_waitcnt lgkmcnt(7)
	v_add_f32_e32 v59, v59, v150
	ds_write_b32 v142, v59
	s_waitcnt lgkmcnt(7)
	v_add_f32_e32 v59, v59, v151
	ds_write_b32 v143, v59
	s_waitcnt lgkmcnt(7)
	v_add_f32_e32 v59, v59, v152
	ds_write_b32 v144, v59
	s_waitcnt lgkmcnt(7)
	v_add_f32_e32 v59, v59, v153
	ds_write_b32 v145, v59
	s_waitcnt lgkmcnt(7)
	v_add_f32_e32 v59, v59, v154
	ds_write_b32 v146, v59
	s_waitcnt lgkmcnt(7)
	v_add_f32_e32 v59, v59, v155
	ds_write_b32 v147, v59
	s_cbranch_scc0 .LBB0_97
	v_lshlrev_b32_e32 v59, 3, v113
	v_lshl_add_u32 v58, v110, 2, 0
	v_add_u32_e32 v60, 32, v59
	v_lshl_add_u32 v61, v60, 9, v58
	s_waitcnt lgkmcnt(0)
	s_barrier
	ds_read2st64_b32 v[56:57], v58 offset0:94 offset1:224
	ds_read_b32 v62, v61 offset:8192
	v_lshlrev_b32_e32 v60, 7, v60
	v_sub_u32_e32 v60, v110, v60
	v_lshl_add_u32 v60, v60, 2, 0
	v_add_u32_e32 v60, 0x11e00, v60
	s_waitcnt lgkmcnt(0)
	v_add_f32_e32 v62, v56, v62
	ds_write_b32 v61, v62 offset:8192
	ds_read_b32 v61, v60
	v_lshlrev_b32_e32 v132, 16, v52
	v_and_b32_e32 v133, 0xffff0000, v52
	s_movk_i32 s4, 0x110
	v_readlane_b32 s5, v255, 9
	s_waitcnt lgkmcnt(0)
	v_add_f32_e32 v61, v57, v61
	ds_write_b32 v60, v61
	v_add_u32_e32 v60, 33, v59
	v_lshl_add_u32 v61, v60, 9, v58
	ds_read_b32 v62, v61 offset:8192
	v_lshlrev_b32_e32 v60, 7, v60
	v_sub_u32_e32 v60, v110, v60
	v_lshl_add_u32 v60, v60, 2, 0
	v_add_u32_e32 v60, 0x11e00, v60
	s_waitcnt lgkmcnt(0)
	v_add_f32_e32 v62, v56, v62
	ds_write_b32 v61, v62 offset:8192
	ds_read_b32 v61, v60
	v_add_u32_e32 v62, 34, v59
	v_lshlrev_b32_e32 v134, 16, v48
	v_and_b32_e32 v135, 0xffff0000, v48
	v_lshlrev_b32_e32 v136, 16, v53
	s_waitcnt lgkmcnt(0)
	v_add_f32_e32 v61, v57, v61
	ds_write_b32 v60, v61
	v_lshl_add_u32 v60, v62, 9, v58
	ds_read_b32 v61, v60 offset:8192
	v_lshlrev_b32_e32 v62, 7, v62
	v_sub_u32_e32 v62, v110, v62
	v_lshl_add_u32 v62, v62, 2, 0
	v_and_b32_e32 v137, 0xffff0000, v53
	s_waitcnt lgkmcnt(0)
	v_add_f32_e32 v61, v56, v61
	ds_write_b32 v60, v61 offset:8192
	v_add_u32_e32 v60, 0x11e00, v62
	ds_read_b32 v61, v60
	v_add_u32_e32 v62, 35, v59
	v_lshl_add_u32 v63, v62, 9, v58
	v_lshlrev_b32_e32 v140, 16, v49
	v_and_b32_e32 v141, 0xffff0000, v49
	s_waitcnt lgkmcnt(0)
	v_add_f32_e32 v61, v57, v61
	ds_write_b32 v60, v61
	ds_read_b32 v60, v63 offset:8192
	v_lshlrev_b32_e32 v61, 7, v62
	v_sub_u32_e32 v61, v110, v61
	v_lshl_add_u32 v61, v61, 2, 0
	v_add_u32_e32 v61, 0x11e00, v61
	s_waitcnt lgkmcnt(0)
	v_add_f32_e32 v60, v56, v60
	ds_write_b32 v63, v60 offset:8192
	ds_read_b32 v60, v61
	v_add_u32_e32 v62, 36, v59
	v_lshl_add_u32 v63, v62, 9, v58
	v_lshlrev_b32_e32 v138, 16, v54
	v_and_b32_e32 v139, 0xffff0000, v54
	s_waitcnt lgkmcnt(0)
	v_add_f32_e32 v60, v57, v60
	ds_write_b32 v61, v60
	ds_read_b32 v60, v63 offset:8192
	v_lshlrev_b32_e32 v61, 7, v62
	v_sub_u32_e32 v61, v110, v61
	v_lshl_add_u32 v61, v61, 2, 0
	v_add_u32_e32 v61, 0x11e00, v61
	s_waitcnt lgkmcnt(0)
	v_add_f32_e32 v60, v56, v60
	ds_write_b32 v63, v60 offset:8192
	ds_read_b32 v60, v61
	v_add_u32_e32 v62, 37, v59
	v_lshl_add_u32 v63, v62, 9, v58
	v_lshlrev_b32_e32 v144, 16, v50
	v_and_b32_e32 v145, 0xffff0000, v50
	s_waitcnt lgkmcnt(0)
	v_add_f32_e32 v60, v57, v60
	ds_write_b32 v61, v60
	ds_read_b32 v60, v63 offset:8192
	v_lshlrev_b32_e32 v61, 7, v62
	v_sub_u32_e32 v61, v110, v61
	v_lshl_add_u32 v61, v61, 2, 0
	v_add_u32_e32 v61, 0x11e00, v61
	s_waitcnt lgkmcnt(0)
	v_add_f32_e32 v60, v56, v60
	ds_write_b32 v63, v60 offset:8192
	ds_read_b32 v60, v61
	v_add_u32_e32 v62, 38, v59
	v_lshl_add_u32 v63, v62, 9, v58
	v_add_u32_e32 v59, 39, v59
	v_lshl_add_u32 v58, v59, 9, v58
	s_waitcnt lgkmcnt(0)
	v_add_f32_e32 v60, v57, v60
	ds_write_b32 v61, v60
	ds_read_b32 v60, v63 offset:8192
	v_lshlrev_b32_e32 v61, 7, v62
	v_sub_u32_e32 v61, v110, v61
	v_lshl_add_u32 v61, v61, 2, 0
	v_add_u32_e32 v61, 0x11e00, v61
	s_waitcnt lgkmcnt(0)
	v_add_f32_e32 v60, v56, v60
	ds_write_b32 v63, v60 offset:8192
	ds_read_b32 v60, v61
	v_lshlrev_b32_e32 v59, 7, v59
	v_sub_u32_e32 v59, v110, v59
	v_lshl_add_u32 v59, v59, 2, 0
	v_add_u32_e32 v59, 0x11e00, v59
	s_waitcnt lgkmcnt(0)
	v_add_f32_e32 v60, v57, v60
	ds_write_b32 v61, v60
	ds_read_b32 v60, v58 offset:8192
	v_lshlrev_b32_e32 v62, 9, v112
	v_mul_lo_u32 v63, v112, s4
	v_readlane_b32 s4, v255, 8
	v_add3_u32 v168, s5, v63, v104
	s_waitcnt lgkmcnt(0)
	v_add_f32_e32 v56, v56, v60
	ds_write_b32 v58, v56 offset:8192
	ds_read_b32 v56, v59
	v_lshlrev_b32_e32 v58, 2, v111
	v_add3_u32 v170, 0, v62, v58
	v_add3_u32 v167, s4, v63, v104
	v_lshlrev_b32_e32 v142, 16, v55
	s_waitcnt lgkmcnt(0)
	v_add_f32_e32 v52, v57, v56
	ds_write_b32 v59, v52
	s_waitcnt lgkmcnt(0)
	s_barrier
	ds_read_b128 v[56:59], v170 offset:8192
	ds_read_b128 v[60:63], v170 offset:8208
	v_and_b32_e32 v143, 0xffff0000, v55
	v_lshlrev_b32_e32 v148, 16, v51
	v_and_b32_e32 v149, 0xffff0000, v51
	s_waitcnt lgkmcnt(1)
	v_mul_f32_e32 v52, 0x3fb8aa3b, v56
	v_mul_f32_e32 v65, 0x3fb8aa3b, v57
	v_exp_f32_e32 v64, v52
	v_exp_f32_e32 v65, v65
	v_mul_f32_e32 v56, 0xbfb8aa3b, v56
	v_mul_f32_e32 v52, 0xbfb8aa3b, v57
	v_mul_f32_e32 v48, 0x3fb8aa3b, v58
	v_pk_mul_f32 v[64:65], v[64:65], v[132:133]
	v_exp_f32_e32 v56, v56
	v_exp_f32_e32 v57, v52
	v_cvt_pk_bf16_f32 v52, v64, v65
	v_exp_f32_e32 v64, v48
	v_mul_f32_e32 v48, 0x3fb8aa3b, v59
	v_mul_f32_e32 v53, 0xbfb8aa3b, v58
	v_exp_f32_e32 v65, v48
	v_exp_f32_e32 v58, v53
	v_mul_f32_e32 v53, 0xbfb8aa3b, v59
	v_exp_f32_e32 v59, v53
	v_pk_mul_f32 v[56:57], v[56:57], v[134:135]
	s_waitcnt lgkmcnt(0)
	v_mul_f32_e32 v49, 0x3fb8aa3b, v60
	v_cvt_pk_bf16_f32 v48, v56, v57
	v_pk_mul_f32 v[56:57], v[64:65], v[136:137]
	v_mul_f32_e32 v54, 0xbfb8aa3b, v60
	v_cvt_pk_bf16_f32 v53, v56, v57
	v_pk_mul_f32 v[56:57], v[58:59], v[140:141]
	v_exp_f32_e32 v58, v49
	v_mul_f32_e32 v49, 0x3fb8aa3b, v61
	v_exp_f32_e32 v59, v49
	v_cvt_pk_bf16_f32 v49, v56, v57
	v_mul_f32_e32 v50, 0x3fb8aa3b, v62
	v_mul_f32_e32 v55, 0xbfb8aa3b, v62
	v_pk_mul_f32 v[56:57], v[58:59], v[138:139]
	v_exp_f32_e32 v58, v54
	v_mul_f32_e32 v54, 0xbfb8aa3b, v61
	v_exp_f32_e32 v59, v54
	v_cvt_pk_bf16_f32 v54, v56, v57
	v_lshlrev_b32_e32 v146, 16, v44
	v_and_b32_e32 v147, 0xffff0000, v44
	v_pk_mul_f32 v[56:57], v[58:59], v[144:145]
	v_exp_f32_e32 v58, v50
	v_mul_f32_e32 v50, 0x3fb8aa3b, v63
	v_exp_f32_e32 v59, v50
	v_cvt_pk_bf16_f32 v50, v56, v57
	v_lshlrev_b32_e32 v152, 16, v40
	v_and_b32_e32 v153, 0xffff0000, v40
	v_pk_mul_f32 v[56:57], v[58:59], v[142:143]
	v_exp_f32_e32 v58, v55
	v_mul_f32_e32 v55, 0xbfb8aa3b, v63
	v_exp_f32_e32 v59, v55
	v_cvt_pk_bf16_f32 v55, v56, v57
	v_lshlrev_b32_e32 v150, 16, v45
	v_and_b32_e32 v151, 0xffff0000, v45
	v_pk_mul_f32 v[56:57], v[58:59], v[148:149]
	v_lshlrev_b32_e32 v156, 16, v41
	v_cvt_pk_bf16_f32 v51, v56, v57
	ds_write_b128 v167, v[52:55]
	ds_write_b128 v168, v[48:51]
	ds_read_b128 v[48:51], v170 offset:8224
	ds_read_b128 v[52:55], v170 offset:8240
	v_and_b32_e32 v157, 0xffff0000, v41
	v_lshlrev_b32_e32 v154, 16, v46
	v_and_b32_e32 v155, 0xffff0000, v46
	s_waitcnt lgkmcnt(1)
	v_mul_f32_e32 v56, 0x3fb8aa3b, v48
	v_mul_f32_e32 v57, 0x3fb8aa3b, v49
	v_exp_f32_e32 v56, v56
	v_exp_f32_e32 v57, v57
	v_mul_f32_e32 v44, 0xbfb8aa3b, v48
	v_exp_f32_e32 v48, v44
	v_mul_f32_e32 v44, 0xbfb8aa3b, v49
	v_pk_mul_f32 v[56:57], v[56:57], v[146:147]
	v_mul_f32_e32 v40, 0x3fb8aa3b, v50
	v_exp_f32_e32 v49, v44
	v_cvt_pk_bf16_f32 v44, v56, v57
	v_exp_f32_e32 v56, v40
	v_mul_f32_e32 v40, 0x3fb8aa3b, v51
	v_mul_f32_e32 v45, 0xbfb8aa3b, v50
	v_exp_f32_e32 v57, v40
	v_exp_f32_e32 v50, v45
	v_mul_f32_e32 v45, 0xbfb8aa3b, v51
	v_exp_f32_e32 v51, v45
	v_pk_mul_f32 v[48:49], v[48:49], v[152:153]
	s_waitcnt lgkmcnt(0)
	v_mul_f32_e32 v41, 0x3fb8aa3b, v52
	v_cvt_pk_bf16_f32 v40, v48, v49
	v_pk_mul_f32 v[48:49], v[56:57], v[150:151]
	v_mul_f32_e32 v46, 0xbfb8aa3b, v52
	v_cvt_pk_bf16_f32 v45, v48, v49
	v_pk_mul_f32 v[48:49], v[50:51], v[156:157]
	v_exp_f32_e32 v50, v41
	v_mul_f32_e32 v41, 0x3fb8aa3b, v53
	v_exp_f32_e32 v51, v41
	v_cvt_pk_bf16_f32 v41, v48, v49
	v_lshlrev_b32_e32 v160, 16, v42
	v_and_b32_e32 v161, 0xffff0000, v42
	v_pk_mul_f32 v[48:49], v[50:51], v[154:155]
	v_exp_f32_e32 v50, v46
	v_mul_f32_e32 v46, 0xbfb8aa3b, v53
	v_exp_f32_e32 v51, v46
	v_mul_f32_e32 v42, 0x3fb8aa3b, v54
	v_cvt_pk_bf16_f32 v46, v48, v49
	v_lshlrev_b32_e32 v158, 16, v47
	v_pk_mul_f32 v[48:49], v[50:51], v[160:161]
	v_exp_f32_e32 v50, v42
	v_mul_f32_e32 v42, 0x3fb8aa3b, v55
	v_exp_f32_e32 v51, v42
	v_and_b32_e32 v159, 0xffff0000, v47
	v_mul_f32_e32 v47, 0xbfb8aa3b, v54
	v_cvt_pk_bf16_f32 v42, v48, v49
	v_pk_mul_f32 v[48:49], v[50:51], v[158:159]
	v_exp_f32_e32 v50, v47
	v_mul_f32_e32 v47, 0xbfb8aa3b, v55
	v_exp_f32_e32 v51, v47
	v_lshlrev_b32_e32 v58, 1, v129
	v_and_b32_e32 v59, 3, v125
	v_lshlrev_b32_e32 v162, 16, v43
	v_and_b32_e32 v163, 0xffff0000, v43
	v_and_or_b32 v58, v58, 24, v59
	v_cvt_pk_bf16_f32 v47, v48, v49
	v_pk_mul_f32 v[48:49], v[50:51], v[162:163]
	v_cmp_gt_u32_e32 vcc, v165, v129
	v_cvt_pk_bf16_f32 v43, v48, v49
	ds_write_b128 v167, v[44:47] offset:16
	ds_write_b128 v168, v[40:43] offset:16
	v_mul_u32_u24_e32 v40, 0x110, v58
	v_add3_u32 v171, s5, v176, v40
	v_mul_u32_u24_e32 v40, 0x110, v129
	v_add3_u32 v169, s4, v176, v40
	s_waitcnt lgkmcnt(0)
	s_barrier
	ds_read_b128 v[44:47], v171
	ds_read_b128 v[88:91], v171 offset:64
	ds_read_b128 v[52:55], v169
	ds_read_b128 v[48:51], v169 offset:64
	ds_read_b128 v[120:123], v171 offset:128
	ds_read_b128 v[172:175], v171 offset:192
	ds_read_b128 v[60:63], v169 offset:128
	ds_read_b128 v[56:59], v169 offset:192
	ds_read_b128 v[186:189], v171 offset:1088
	ds_read_b128 v[194:197], v171 offset:1152
	ds_read_b128 v[198:201], v171 offset:1216
	ds_read_b128 v[202:205], v171 offset:1280
	ds_read_b128 v[80:83], v169 offset:4352
	ds_read_b128 v[68:71], v169 offset:4416
	s_waitcnt lgkmcnt(1)
	v_mfma_f32_16x16x32_bf16 v[64:67], v[44:47], v[80:83], 0
	v_cmp_lt_u32_e64 s[4:5], v165, v129
	v_or_b32_e32 v166, v126, v129
	v_mul_lo_u32 v166, v166, s15
	s_waitcnt lgkmcnt(0)
	v_mfma_f32_16x16x32_bf16 v[76:79], v[88:91], v[68:71], v[64:67]
	ds_read_b128 v[72:75], v169 offset:4480
	s_nop 1
	ds_read_b128 v[64:67], v169 offset:4544
	ds_read_b128 v[108:111], v169 offset:8704
	ds_read_b128 v[84:87], v169 offset:8768
	v_or_b32_e32 v218, 4, v165
	s_waitcnt lgkmcnt(3)
	v_mfma_f32_16x16x32_bf16 v[76:79], v[120:123], v[72:75], v[76:79]
	v_or_b32_e32 v230, 5, v165
	v_or_b32_e32 v231, 6, v165
	v_or_b32_e32 v235, 7, v165
	s_waitcnt lgkmcnt(2)
	v_mfma_f32_16x16x32_bf16 v[112:115], v[172:175], v[64:67], v[76:79]
	v_cmp_gt_u32_e64 s[10:11], v218, v129
	v_cmp_gt_u32_e64 s[18:19], v230, v129
	v_cmp_gt_u32_e64 s[24:25], v231, v129
	v_mfma_f32_16x16x32_bf16 v[76:79], v[186:189], v[80:83], 0
	v_cmp_gt_u32_e64 s[64:65], v235, v129
	s_mov_b32 s15, s93
	s_mov_b32 s12, s93
	v_mfma_f32_16x16x32_bf16 v[76:79], v[194:197], v[68:71], v[76:79]
	s_mov_b32 s13, s93
	s_mov_b32 s68, 0x10000
	s_lshl_b32 s92, s92, 1
	v_mfma_f32_16x16x32_bf16 v[76:79], v[198:201], v[72:75], v[76:79]
	v_mfma_f32_16x16x32_bf16 v[116:119], v[202:205], v[64:67], v[76:79]
	s_waitcnt lgkmcnt(1)
	v_mfma_f32_16x16x32_bf16 v[76:79], v[44:47], v[108:111], 0
	s_waitcnt lgkmcnt(0)
	v_mfma_f32_16x16x32_bf16 v[92:95], v[88:91], v[84:87], v[76:79]
	ds_read_b128 v[104:107], v169 offset:8832
	s_nop 4
	ds_read_b128 v[76:79], v169 offset:8896
	ds_read_b128 v[100:103], v169 offset:13056
	ds_read_b128 v[96:99], v169 offset:13120
	s_waitcnt lgkmcnt(3)
	v_mfma_f32_16x16x32_bf16 v[92:95], v[120:123], v[104:107], v[92:95]
	s_waitcnt lgkmcnt(2)
	v_mfma_f32_16x16x32_bf16 v[206:209], v[172:175], v[76:79], v[92:95]
	v_mfma_f32_16x16x32_bf16 v[92:95], v[186:189], v[108:111], 0
	v_mfma_f32_16x16x32_bf16 v[92:95], v[194:197], v[84:87], v[92:95]
	v_mfma_f32_16x16x32_bf16 v[40:43], v[44:47], v[52:55], 0
	v_mfma_f32_16x16x32_bf16 v[92:95], v[198:201], v[104:107], v[92:95]
	s_waitcnt lgkmcnt(1)
	v_mfma_f32_16x16x32_bf16 v[44:47], v[44:47], v[100:103], 0
	v_mfma_f32_16x16x32_bf16 v[40:43], v[88:91], v[48:51], v[40:43]
	v_mfma_f32_16x16x32_bf16 v[210:213], v[202:205], v[76:79], v[92:95]
	s_waitcnt lgkmcnt(0)
	v_mfma_f32_16x16x32_bf16 v[44:47], v[88:91], v[96:99], v[44:47]
	s_nop 1
	ds_read_b128 v[92:95], v169 offset:13184
	ds_read_b128 v[88:91], v169 offset:13248
	ds_read_b128 v[214:217], v171 offset:9792
	ds_read_b128 v[236:239], v171 offset:9856
	s_waitcnt lgkmcnt(3)
	v_mfma_f32_16x16x32_bf16 v[44:47], v[120:123], v[92:95], v[44:47]
	ds_read_b128 v[244:247], v171 offset:9920
	ds_read_b128 v[248:251], v171 offset:9984
	v_mfma_f32_16x16x32_bf16 v[40:43], v[120:123], v[60:63], v[40:43]
	s_waitcnt lgkmcnt(4)
	v_mfma_f32_16x16x32_bf16 v[120:123], v[172:175], v[88:91], v[44:47]
	v_mfma_f32_16x16x32_bf16 v[44:47], v[186:189], v[100:103], 0
	v_mfma_f32_16x16x32_bf16 v[44:47], v[194:197], v[96:99], v[44:47]
	v_mfma_f32_16x16x32_bf16 v[190:193], v[172:175], v[56:59], v[40:43]
	ds_read_b128 v[172:175], v171 offset:8704
	v_mfma_f32_16x16x32_bf16 v[40:43], v[186:189], v[52:55], 0
	v_mfma_f32_16x16x32_bf16 v[44:47], v[198:201], v[92:95], v[44:47]
	s_nop 4
	v_cndmask_b32_e64 v219, v190, 0, vcc
	v_cndmask_b32_e64 v228, 0, v191, s[4:5]
	v_mfma_f32_16x16x32_bf16 v[40:43], v[194:197], v[48:51], v[40:43]
	v_mfma_f32_16x16x32_bf16 v[186:189], v[202:205], v[88:91], v[44:47]
	s_nop 2
	ds_read_b128 v[44:47], v171 offset:8768
	v_mfma_f32_16x16x32_bf16 v[40:43], v[198:201], v[60:63], v[40:43]
	ds_read_b128 v[198:201], v171 offset:8832
	s_waitcnt lgkmcnt(2)
	v_mfma_f32_16x16x32_bf16 v[194:197], v[172:175], v[108:111], 0
	v_mfma_f32_16x16x32_bf16 v[172:175], v[172:175], v[100:103], 0
	v_mfma_f32_16x16x32_bf16 v[40:43], v[202:205], v[56:59], v[40:43]
	ds_read_b128 v[202:205], v171 offset:8896
	s_waitcnt lgkmcnt(2)
	v_mfma_f32_16x16x32_bf16 v[194:197], v[44:47], v[84:87], v[194:197]
	v_mfma_f32_16x16x32_bf16 v[44:47], v[44:47], v[96:99], v[172:175]
	s_nop 3
	v_cndmask_b32_e64 v40, v40, 0, s[10:11]
	v_cndmask_b32_e64 v41, v41, 0, s[18:19]
	v_cndmask_b32_e64 v42, v42, 0, s[24:25]
	s_waitcnt lgkmcnt(1)
	v_mfma_f32_16x16x32_bf16 v[44:47], v[198:201], v[92:95], v[44:47]
	v_or_b32_e32 v173, 2, v165
	v_or_b32_e32 v175, 3, v165
	v_cmp_gt_u32_e64 s[8:9], v173, v129
	v_cmp_gt_u32_e64 s[6:7], v175, v129
	v_mfma_f32_16x16x32_bf16 v[240:243], v[214:217], v[108:111], 0
	v_cndmask_b32_e64 v174, v192, 0, s[8:9]
	v_cndmask_b32_e64 v229, v193, 0, s[6:7]
	v_add3_u32 v172, s14, v176, v166
	s_waitcnt lgkmcnt(0)
	v_mfma_f32_16x16x32_bf16 v[190:193], v[202:205], v[88:91], v[44:47]
	v_cndmask_b32_e64 v43, v43, 0, s[64:65]
	s_mov_b32 s14, s93
	v_or_b32_e32 v166, 16, v129
	v_mfma_f32_16x16x32_bf16 v[44:47], v[214:217], v[100:103], 0
	ds_read_b128 v[214:217], v172 offset:64
	v_cmp_gt_u32_e64 s[16:17], v173, v166
	v_cmp_gt_u32_e64 s[20:21], v175, v166
	v_mfma_f32_16x16x32_bf16 v[240:243], v[236:239], v[84:87], v[240:243]
	v_cmp_gt_u32_e64 s[22:23], v218, v166
	v_cmp_gt_u32_e64 s[26:27], v230, v166
	v_cmp_gt_u32_e64 s[28:29], v231, v166
	v_mfma_f32_16x16x32_bf16 v[44:47], v[236:239], v[96:99], v[44:47]
	v_cmp_gt_u32_e64 s[30:31], v235, v166
	v_cndmask_b32_e64 v114, v114, 0, s[16:17]
	v_cndmask_b32_e64 v115, v115, 0, s[20:21]
	v_mfma_f32_16x16x32_bf16 v[194:197], v[198:201], v[104:107], v[194:197]
	ds_read_b128 v[198:201], v172
	v_cndmask_b32_e64 v116, v116, 0, s[22:23]
	v_cndmask_b32_e64 v117, v117, 0, s[26:27]
	v_mfma_f32_16x16x32_bf16 v[240:243], v[244:247], v[104:107], v[240:243]
	v_cndmask_b32_e64 v118, v118, 0, s[28:29]
	v_or_b32_e32 v173, 36, v165
	v_or_b32_e32 v175, 34, v165
	v_mfma_f32_16x16x32_bf16 v[44:47], v[244:247], v[92:95], v[44:47]
	ds_read_b128 v[244:247], v172 offset:2304
	v_or_b32_e32 v176, 35, v165
	v_mfma_f32_16x16x32_bf16 v[240:243], v[248:251], v[76:79], v[240:243]
	v_mfma_f32_16x16x32_bf16 v[236:239], v[248:251], v[88:91], v[44:47]
	ds_read_b128 v[248:251], v172 offset:2368
	v_mfma_f32_16x16x32_bf16 v[194:197], v[202:205], v[76:79], v[194:197]
	v_cvt_pk_bf16_f32 v202, v219, v228
	v_cvt_pk_bf16_f32 v203, v174, v229
	v_cvt_pk_bf16_f32 v204, v40, v41
	v_cvt_pk_bf16_f32 v205, v42, v43
	v_mov_b64_e32 v[42:43], s[14:15]
	v_mov_b64_e32 v[40:41], s[12:13]
	s_waitcnt lgkmcnt(2)
	v_mfma_f32_16x16x32_bf16 v[44:47], v[198:201], v[202:205], 0
	v_cmp_gt_u32_e64 s[12:13], v165, v166
	v_cmp_lt_u32_e64 s[14:15], v165, v166
	v_or_b32_e32 v174, 33, v165
	s_waitcnt lgkmcnt(1)
	v_mfma_f32_16x16x32_bf16 v[202:205], v[244:247], v[202:205], 0
	v_cndmask_b32_e64 v112, v112, 0, s[12:13]
	v_cndmask_b32_e64 v113, 0, v113, s[14:15]
	v_mfma_f32_16x16x32_bf16 v[44:47], v[214:217], v[40:43], v[44:47]
	s_waitcnt lgkmcnt(0)
	v_mfma_f32_16x16x32_bf16 v[202:205], v[248:251], v[40:43], v[202:205]
	v_mfma_f32_16x16x32_bf16 v[44:47], v[36:39], v[52:55], v[44:47]
	v_mfma_f32_16x16x32_bf16 v[52:55], v[20:23], v[52:55], v[202:205]
	v_mfma_f32_16x16x32_bf16 v[44:47], v[32:35], v[48:51], v[44:47]
	s_nop 4
	v_or_b32_e32 v202, 37, v165
	v_or_b32_e32 v203, 38, v165
	v_or_b32_e32 v204, 39, v165
	v_mfma_f32_16x16x32_bf16 v[48:51], v[16:19], v[48:51], v[52:55]
	v_mfma_f32_16x16x32_bf16 v[44:47], v[28:31], v[60:63], v[44:47]
	v_mfma_f32_16x16x32_bf16 v[48:51], v[12:15], v[60:63], v[48:51]
	v_cndmask_b32_e64 v63, v119, 0, s[30:31]
	v_cvt_pk_bf16_f32 v60, v112, v113
	v_cvt_pk_bf16_f32 v61, v114, v115
	v_cvt_pk_bf16_f32 v62, v116, v117
	v_cvt_pk_bf16_f32 v63, v118, v63
	v_mfma_f32_16x16x32_bf16 v[44:47], v[24:27], v[56:59], v[44:47]
	v_or_b32_e32 v113, 32, v129
	v_cmp_gt_u32_e64 s[34:35], v174, v113
	v_cmp_gt_u32_e64 s[36:37], v175, v113
	v_mfma_f32_16x16x32_bf16 v[52:55], v[8:11], v[56:59], v[48:51]
	v_cmp_gt_u32_e64 s[38:39], v176, v113
	v_cmp_gt_u32_e64 s[40:41], v173, v113
	v_cmp_gt_u32_e64 s[42:43], v202, v113
	v_mfma_f32_16x16x32_bf16 v[48:51], v[198:201], v[60:63], 0
	v_cmp_gt_u32_e64 s[44:45], v203, v113
	v_cmp_gt_u32_e64 s[46:47], v204, v113
	v_cvt_pk_bf16_f32 v114, v206, v207
	v_mfma_f32_16x16x32_bf16 v[56:59], v[244:247], v[60:63], 0
	v_cvt_pk_bf16_f32 v115, v208, v209
	v_cvt_pk_bf16_f32 v116, v210, v211
	v_cvt_pk_bf16_f32 v117, v212, v213
	v_mfma_f32_16x16x32_bf16 v[48:51], v[214:217], v[40:43], v[48:51]
	v_cndmask_b32_e64 v60, v194, 0, vcc
	v_cndmask_b32_e64 v61, v195, 0, s[34:35]
	v_cndmask_b32_e64 v62, v196, 0, s[36:37]
	v_mfma_f32_16x16x32_bf16 v[56:59], v[248:251], v[40:43], v[56:59]
	v_cndmask_b32_e64 v63, v197, 0, s[38:39]
	v_cvt_pk_bf16_f32 v60, v60, v61
	v_cvt_pk_bf16_f32 v61, v62, v63
	v_mfma_f32_16x16x32_bf16 v[48:51], v[36:39], v[80:83], v[48:51]
	v_cvt_pk_bf16_f32 v118, v120, v121
	v_cvt_pk_bf16_f32 v119, v122, v123
	v_cvt_pk_bf16_f32 v120, v186, v187
	v_mfma_f32_16x16x32_bf16 v[56:59], v[20:23], v[80:83], v[56:59]
	v_cvt_pk_bf16_f32 v121, v188, v189
	v_or_b32_e32 v112, 48, v129
	v_cmp_gt_u32_e64 s[50:51], v174, v112
	v_mfma_f32_16x16x32_bf16 v[48:51], v[32:35], v[68:71], v[48:51]
	v_cmp_gt_u32_e64 s[52:53], v175, v112
	v_cmp_gt_u32_e64 s[54:55], v176, v112
	v_cmp_gt_u32_e64 s[56:57], v173, v112
	v_mfma_f32_16x16x32_bf16 v[56:59], v[16:19], v[68:71], v[56:59]
	v_cndmask_b32_e64 v68, v240, 0, s[40:41]
	v_cndmask_b32_e64 v69, v241, 0, s[42:43]
	v_cndmask_b32_e64 v70, v242, 0, s[44:45]
	v_mfma_f32_16x16x32_bf16 v[48:51], v[28:31], v[72:75], v[48:51]
	v_cndmask_b32_e64 v71, v243, 0, s[46:47]
	v_cvt_pk_bf16_f32 v62, v68, v69
	v_cvt_pk_bf16_f32 v63, v70, v71
	v_mfma_f32_16x16x32_bf16 v[56:59], v[12:15], v[72:75], v[56:59]
	v_cmp_gt_u32_e64 s[58:59], v202, v112
	v_cmp_gt_u32_e64 s[60:61], v203, v112
	v_cmp_gt_u32_e64 s[62:63], v204, v112
	v_mfma_f32_16x16x32_bf16 v[48:51], v[24:27], v[64:67], v[48:51]
	v_cndmask_b32_e64 v72, v236, 0, s[56:57]
	v_cndmask_b32_e64 v73, v237, 0, s[58:59]
	v_cndmask_b32_e64 v74, v238, 0, s[60:61]
	v_mfma_f32_16x16x32_bf16 v[64:67], v[8:11], v[64:67], v[56:59]
	v_cndmask_b32_e64 v75, v239, 0, s[62:63]
	v_mfma_f32_16x16x32_bf16 v[56:59], v[198:201], v[114:117], 0
	v_mfma_f32_16x16x32_bf16 v[68:71], v[244:247], v[114:117], 0
	v_mfma_f32_16x16x32_bf16 v[56:59], v[214:217], v[60:63], v[56:59]
	v_mfma_f32_16x16x32_bf16 v[60:63], v[248:251], v[60:63], v[68:71]
	v_mfma_f32_16x16x32_bf16 v[60:63], v[20:23], v[108:111], v[60:63]
	s_nop 4
	v_or_b32_e32 v68, 32, v165
	v_cmp_gt_u32_e64 s[48:49], v68, v112
	v_cndmask_b32_e64 v69, v191, 0, s[50:51]
	v_mfma_f32_16x16x32_bf16 v[60:63], v[16:19], v[84:87], v[60:63]
	v_cndmask_b32_e64 v68, v190, 0, s[48:49]
	v_cndmask_b32_e64 v70, v192, 0, s[52:53]
	v_cndmask_b32_e64 v71, v193, 0, s[54:55]
	v_mfma_f32_16x16x32_bf16 v[56:59], v[36:39], v[108:111], v[56:59]
	v_mfma_f32_16x16x32_bf16 v[60:63], v[12:15], v[104:107], v[60:63]
	v_mfma_f32_16x16x32_bf16 v[56:59], v[32:35], v[84:87], v[56:59]
	v_mfma_f32_16x16x32_bf16 v[80:83], v[8:11], v[76:79], v[60:63]
	v_mfma_f32_16x16x32_bf16 v[60:63], v[198:201], v[118:121], 0
	v_mfma_f32_16x16x32_bf16 v[56:59], v[28:31], v[104:107], v[56:59]
	v_cvt_pk_bf16_f32 v104, v68, v69
	v_cvt_pk_bf16_f32 v105, v70, v71
	v_cvt_pk_bf16_f32 v106, v72, v73
	v_cvt_pk_bf16_f32 v107, v74, v75
	v_mfma_f32_16x16x32_bf16 v[56:59], v[24:27], v[76:79], v[56:59]
	s_nop 0
	v_mfma_f32_16x16x32_bf16 v[60:63], v[214:217], v[104:107], v[60:63]
	v_mfma_f32_16x16x32_bf16 v[36:39], v[36:39], v[100:103], v[60:63]
	v_mfma_f32_16x16x32_bf16 v[32:35], v[32:35], v[96:99], v[36:39]
	s_nop 5
	v_add_co_u32_e64 v60, s[68:69], s68, v130
	s_nop 1
	v_addc_co_u32_e64 v61, s[68:69], 0, v131, s[68:69]
	v_mfma_f32_16x16x32_bf16 v[28:31], v[28:31], v[92:95], v[32:35]
	s_mov_b32 s68, 0x11000
	v_add_co_u32_e64 v108, s[68:69], s68, v130
	global_load_dwordx4 v[72:75], v[60:61], off offset:1024
	global_load_dwordx4 v[68:71], v[60:61], off offset:2048
	v_addc_co_u32_e64 v109, s[68:69], 0, v131, s[68:69]
	global_load_dwordx4 v[60:63], v[60:61], off offset:3072
	s_nop 0
	global_load_dwordx4 v[76:79], v[108:109], off offset:-4096
	global_load_dwordx4 v[36:39], v[108:109], off
	v_mfma_f32_16x16x32_bf16 v[84:87], v[24:27], v[88:91], v[28:31]
	global_load_dwordx4 v[32:35], v[108:109], off offset:1024
	s_nop 1
	global_load_dwordx4 v[28:31], v[108:109], off offset:2048
	global_load_dwordx4 v[24:27], v[108:109], off offset:3072
	s_barrier
	ds_read_b128 v[114:117], v170 offset:40960
	v_mfma_f32_16x16x32_bf16 v[108:111], v[244:247], v[118:121], 0
	v_mfma_f32_16x16x32_bf16 v[104:107], v[248:251], v[104:107], v[108:111]
	v_mfma_f32_16x16x32_bf16 v[20:23], v[20:23], v[100:103], v[104:107]
	s_nop 5
	ds_read_b128 v[108:111], v170 offset:40976
	s_waitcnt lgkmcnt(1)
	v_mul_f32_e32 v118, 0x3fb8aa3b, v114
	v_mul_f32_e32 v119, 0x3fb8aa3b, v115
	v_exp_f32_e32 v118, v118
	v_exp_f32_e32 v119, v119
	v_mul_f32_e32 v114, 0xbfb8aa3b, v114
	v_mul_f32_e32 v115, 0xbfb8aa3b, v115
	v_exp_f32_e32 v114, v114
	v_pk_mul_f32 v[100:101], v[118:119], v[132:133]
	v_exp_f32_e32 v115, v115
	v_cvt_pk_bf16_f32 v100, v100, v101
	v_mul_f32_e32 v101, 0x3fb8aa3b, v116
	v_exp_f32_e32 v106, v101
	v_mul_f32_e32 v101, 0x3fb8aa3b, v117
	v_exp_f32_e32 v107, v101
	v_mul_f32_e32 v101, 0xbfb8aa3b, v116
	v_pk_mul_f32 v[102:103], v[114:115], v[134:135]
	v_exp_f32_e32 v114, v101
	v_mul_f32_e32 v101, 0xbfb8aa3b, v117
	s_waitcnt lgkmcnt(0)
	v_mul_f32_e32 v105, 0x3fb8aa3b, v108
	v_exp_f32_e32 v115, v101
	v_cvt_pk_bf16_f32 v104, v102, v103
	v_pk_mul_f32 v[102:103], v[106:107], v[136:137]
	v_exp_f32_e32 v106, v105
	v_mul_f32_e32 v105, 0x3fb8aa3b, v109
	v_exp_f32_e32 v107, v105
	v_mul_f32_e32 v105, 0xbfb8aa3b, v108
	v_exp_f32_e32 v108, v105
	v_mul_f32_e32 v105, 0xbfb8aa3b, v109
	v_exp_f32_e32 v109, v105
	v_cvt_pk_bf16_f32 v101, v102, v103
	v_pk_mul_f32 v[102:103], v[114:115], v[140:141]
	v_mfma_f32_16x16x32_bf16 v[16:19], v[16:19], v[96:99], v[20:23]
	v_cvt_pk_bf16_f32 v105, v102, v103
	v_pk_mul_f32 v[102:103], v[106:107], v[138:139]
	v_pk_mul_f32 v[106:107], v[108:109], v[144:145]
	v_cvt_pk_bf16_f32 v102, v102, v103
	v_mul_f32_e32 v103, 0x3fb8aa3b, v110
	v_exp_f32_e32 v108, v103
	v_mul_f32_e32 v103, 0x3fb8aa3b, v111
	v_exp_f32_e32 v109, v103
	v_mul_f32_e32 v103, 0xbfb8aa3b, v110
	v_exp_f32_e32 v110, v103
	v_mul_f32_e32 v103, 0xbfb8aa3b, v111
	v_exp_f32_e32 v111, v103
	v_pk_mul_f32 v[108:109], v[108:109], v[142:143]
	v_cvt_pk_bf16_f32 v106, v106, v107
	v_cvt_pk_bf16_f32 v103, v108, v109
	v_pk_mul_f32 v[108:109], v[110:111], v[148:149]
	v_mfma_f32_16x16x32_bf16 v[12:15], v[12:15], v[92:95], v[16:19]
	v_cvt_pk_bf16_f32 v107, v108, v109
	ds_write_b128 v167, v[100:103]
	ds_write_b128 v168, v[104:107]
	ds_read_b128 v[100:103], v170 offset:40992
	ds_read_b128 v[20:23], v170 offset:41008
	v_mfma_f32_16x16x32_bf16 v[8:11], v[8:11], v[88:91], v[12:15]
	s_waitcnt lgkmcnt(1)
	v_mul_f32_e32 v96, 0x3fb8aa3b, v100
	v_mul_f32_e32 v97, 0x3fb8aa3b, v101
	v_exp_f32_e32 v96, v96
	v_exp_f32_e32 v97, v97
	v_mul_f32_e32 v98, 0xbfb8aa3b, v100
	v_mul_f32_e32 v99, 0xbfb8aa3b, v101
	v_exp_f32_e32 v98, v98
	v_pk_mul_f32 v[16:17], v[96:97], v[146:147]
	v_exp_f32_e32 v99, v99
	v_cvt_pk_bf16_f32 v16, v16, v17
	v_mul_f32_e32 v17, 0x3fb8aa3b, v102
	v_exp_f32_e32 v94, v17
	v_mul_f32_e32 v17, 0x3fb8aa3b, v103
	v_exp_f32_e32 v95, v17
	v_mul_f32_e32 v17, 0xbfb8aa3b, v102
	v_pk_mul_f32 v[18:19], v[98:99], v[152:153]
	v_exp_f32_e32 v96, v17
	v_mul_f32_e32 v17, 0xbfb8aa3b, v103
	s_waitcnt lgkmcnt(0)
	v_mul_f32_e32 v93, 0x3fb8aa3b, v20
	v_exp_f32_e32 v97, v17
	v_cvt_pk_bf16_f32 v92, v18, v19
	v_pk_mul_f32 v[18:19], v[94:95], v[150:151]
	v_exp_f32_e32 v94, v93
	v_mul_f32_e32 v93, 0x3fb8aa3b, v21
	v_exp_f32_e32 v95, v93
	v_cvt_pk_bf16_f32 v17, v18, v19
	v_pk_mul_f32 v[18:19], v[96:97], v[156:157]
	v_mul_f32_e32 v20, 0xbfb8aa3b, v20
	v_cvt_pk_bf16_f32 v93, v18, v19
	v_pk_mul_f32 v[18:19], v[94:95], v[154:155]
	v_mul_f32_e32 v21, 0xbfb8aa3b, v21
	v_cvt_pk_bf16_f32 v18, v18, v19
	v_mul_f32_e32 v19, 0x3fb8aa3b, v22
	v_exp_f32_e32 v96, v19
	v_mul_f32_e32 v19, 0x3fb8aa3b, v23
	v_exp_f32_e32 v20, v20
	v_exp_f32_e32 v21, v21
	v_exp_f32_e32 v97, v19
	v_mul_f32_e32 v19, 0xbfb8aa3b, v22
	v_exp_f32_e32 v22, v19
	v_mul_f32_e32 v19, 0xbfb8aa3b, v23
	v_exp_f32_e32 v23, v19
	v_pk_mul_f32 v[20:21], v[20:21], v[160:161]
	s_nop 0
	v_cvt_pk_bf16_f32 v94, v20, v21
	v_pk_mul_f32 v[20:21], v[96:97], v[158:159]
	s_nop 0
	v_cvt_pk_bf16_f32 v19, v20, v21
	v_pk_mul_f32 v[20:21], v[22:23], v[162:163]
	s_nop 0
	v_cvt_pk_bf16_f32 v95, v20, v21
	ds_write_b128 v167, v[16:19] offset:16
	ds_write_b128 v168, v[92:95] offset:16
	s_waitcnt lgkmcnt(0)
	s_barrier
	ds_read_b128 v[104:107], v171
	ds_read_b128 v[88:91], v171 offset:64
	ds_read_b128 v[16:19], v169
	ds_read_b128 v[12:15], v169 offset:64
	s_waitcnt lgkmcnt(1)
	v_mfma_f32_16x16x32_bf16 v[20:23], v[104:107], v[16:19], 0
	ds_read_b128 v[108:111], v171 offset:128
	ds_read_b128 v[114:117], v171 offset:192
	s_waitcnt lgkmcnt(2)
	v_mfma_f32_16x16x32_bf16 v[96:99], v[88:91], v[12:15], v[20:23]
	ds_read_b128 v[92:95], v169 offset:128
	s_nop 2
	ds_read_b128 v[20:23], v169 offset:192
	ds_read_b128 v[118:121], v171 offset:1088
	ds_read_b128 v[134:137], v171 offset:1152
	s_waitcnt lgkmcnt(3)
	v_mfma_f32_16x16x32_bf16 v[96:99], v[108:111], v[92:95], v[96:99]
	ds_read_b128 v[138:141], v171 offset:1216
	ds_read_b128 v[142:145], v171 offset:1280
	s_waitcnt lgkmcnt(4)
	v_mfma_f32_16x16x32_bf16 v[130:133], v[114:117], v[20:23], v[96:99]
	s_waitcnt lgkmcnt(3)
	v_mfma_f32_16x16x32_bf16 v[96:99], v[118:121], v[16:19], 0
	s_waitcnt lgkmcnt(2)
	v_mfma_f32_16x16x32_bf16 v[96:99], v[134:137], v[12:15], v[96:99]
	s_nop 3
	v_cndmask_b32_e32 v122, 0, v130, vcc
	v_cndmask_b32_e64 v123, v131, 0, s[4:5]
	s_waitcnt lgkmcnt(1)
	v_mfma_f32_16x16x32_bf16 v[96:99], v[138:141], v[92:95], v[96:99]
	s_waitcnt lgkmcnt(0)
	v_mfma_f32_16x16x32_bf16 v[146:149], v[142:145], v[20:23], v[96:99]
	s_nop 5
	ds_read_b128 v[96:99], v169 offset:4352
	ds_read_b128 v[100:103], v169 offset:4416
	v_cndmask_b32_e64 v162, 0, v147, s[18:19]
	s_waitcnt lgkmcnt(1)
	v_mfma_f32_16x16x32_bf16 v[104:107], v[104:107], v[96:99], 0
	s_waitcnt lgkmcnt(0)
	v_mfma_f32_16x16x32_bf16 v[88:91], v[88:91], v[100:103], v[104:107]
	ds_read_b128 v[150:153], v169 offset:4480
	s_nop 4
	ds_read_b128 v[104:107], v169 offset:4544
	ds_read_b128 v[154:157], v171 offset:9792
	ds_read_b128 v[158:161], v171 offset:9856
	s_waitcnt lgkmcnt(3)
	v_mfma_f32_16x16x32_bf16 v[88:91], v[108:111], v[150:153], v[88:91]
	ds_read_b128 v[190:193], v171 offset:9920
	ds_read_b128 v[194:197], v171 offset:9984
	s_waitcnt lgkmcnt(4)
	v_mfma_f32_16x16x32_bf16 v[108:111], v[114:117], v[104:107], v[88:91]
	ds_read_b128 v[114:117], v171 offset:8704
	v_mfma_f32_16x16x32_bf16 v[88:91], v[118:121], v[96:99], 0
	v_mfma_f32_16x16x32_bf16 v[88:91], v[134:137], v[100:103], v[88:91]
	v_mfma_f32_16x16x32_bf16 v[88:91], v[138:141], v[150:153], v[88:91]
	ds_read_b128 v[138:141], v171 offset:8832
	v_mfma_f32_16x16x32_bf16 v[118:121], v[142:145], v[104:107], v[88:91]
	ds_read_b128 v[142:145], v171 offset:8896
	s_nop 4
	ds_read_b128 v[88:91], v171 offset:8768
	ds_read_b128 v[206:209], v169 offset:8704
	ds_read_b128 v[210:213], v169 offset:8768
	ds_read_b128 v[236:239], v169 offset:8832
	ds_read_b128 v[240:243], v169 offset:8896
	ds_read_b128 v[248:251], v169 offset:13056
	ds_read_b128 v[228:231], v169 offset:13120
	s_waitcnt lgkmcnt(9)
	v_mfma_f32_16x16x32_bf16 v[134:137], v[114:117], v[16:19], 0
	v_mfma_f32_16x16x32_bf16 v[198:201], v[114:117], v[96:99], 0
	s_waitcnt lgkmcnt(5)
	v_mfma_f32_16x16x32_bf16 v[214:217], v[114:117], v[206:209], 0
	s_waitcnt lgkmcnt(1)
	v_mfma_f32_16x16x32_bf16 v[114:117], v[114:117], v[248:251], 0
	v_mfma_f32_16x16x32_bf16 v[134:137], v[88:91], v[12:15], v[134:137]
	v_mfma_f32_16x16x32_bf16 v[198:201], v[88:91], v[100:103], v[198:201]
	v_mfma_f32_16x16x32_bf16 v[214:217], v[88:91], v[210:213], v[214:217]
	s_waitcnt lgkmcnt(0)
	v_mfma_f32_16x16x32_bf16 v[88:91], v[88:91], v[228:231], v[114:117]
	s_nop 2
	ds_read_b128 v[114:117], v169 offset:13184
	ds_read_b128 v[168:171], v169 offset:13248
	v_mfma_f32_16x16x32_bf16 v[134:137], v[138:141], v[92:95], v[134:137]
	v_mfma_f32_16x16x32_bf16 v[186:189], v[154:157], v[16:19], 0
	v_mfma_f32_16x16x32_bf16 v[198:201], v[138:141], v[150:153], v[198:201]
	v_mfma_f32_16x16x32_bf16 v[214:217], v[138:141], v[236:239], v[214:217]
	s_waitcnt lgkmcnt(1)
	v_mfma_f32_16x16x32_bf16 v[88:91], v[138:141], v[114:117], v[88:91]
	v_mfma_f32_16x16x32_bf16 v[134:137], v[142:145], v[20:23], v[134:137]
	v_mfma_f32_16x16x32_bf16 v[186:189], v[158:161], v[12:15], v[186:189]
	v_mfma_f32_16x16x32_bf16 v[198:201], v[142:145], v[104:107], v[198:201]
	s_nop 5
	v_cvt_pk_bf16_f32 v134, v134, v135
	v_cvt_pk_bf16_f32 v135, v136, v137
	v_mfma_f32_16x16x32_bf16 v[202:205], v[154:157], v[96:99], 0
	v_mfma_f32_16x16x32_bf16 v[214:217], v[142:145], v[240:243], v[214:217]
	v_mfma_f32_16x16x32_bf16 v[244:247], v[154:157], v[206:209], 0
	s_waitcnt lgkmcnt(0)
	v_mfma_f32_16x16x32_bf16 v[138:141], v[142:145], v[168:171], v[88:91]
	v_cndmask_b32_e64 v143, 0, v132, s[8:9]
	v_cndmask_b32_e64 v144, 0, v133, s[6:7]
	ds_read_b128 v[130:133], v172
	v_mfma_f32_16x16x32_bf16 v[88:91], v[154:157], v[248:251], 0
	v_cndmask_b32_e64 v145, 0, v146, s[10:11]
	v_cvt_pk_bf16_f32 v142, v122, v123
	v_cvt_pk_bf16_f32 v143, v143, v144
	v_mfma_f32_16x16x32_bf16 v[186:189], v[190:193], v[92:95], v[186:189]
	v_cvt_pk_bf16_f32 v144, v145, v162
	v_mfma_f32_16x16x32_bf16 v[202:205], v[158:161], v[100:103], v[202:205]
	v_mfma_f32_16x16x32_bf16 v[244:247], v[158:161], v[210:213], v[244:247]
	v_mfma_f32_16x16x32_bf16 v[88:91], v[158:161], v[228:231], v[88:91]
	v_cndmask_b32_e64 v158, 0, v148, s[24:25]
	v_cndmask_b32_e64 v159, 0, v149, s[64:65]
	ds_read_b128 v[146:149], v172 offset:64
	v_mfma_f32_16x16x32_bf16 v[186:189], v[194:197], v[20:23], v[186:189]
	v_cvt_pk_bf16_f32 v145, v158, v159
	ds_read_b128 v[158:161], v172 offset:2304
	ds_read_b128 v[172:175], v172 offset:2368
	s_waitcnt lgkmcnt(3)
	v_mfma_f32_16x16x32_bf16 v[44:47], v[130:133], v[142:145], v[44:47]
	s_mov_b64 s[64:65], s[2:3]
	s_nop 1
	v_cvt_pk_bf16_f32 v136, v186, v187
	v_cvt_pk_bf16_f32 v137, v188, v189
	v_mfma_f32_16x16x32_bf16 v[88:91], v[190:193], v[114:117], v[88:91]
	s_waitcnt lgkmcnt(2)
	v_mfma_f32_16x16x32_bf16 v[44:47], v[146:149], v[134:137], v[44:47]
	s_waitcnt vmcnt(4)
	v_mfma_f32_16x16x32_bf16 v[44:47], v[76:79], v[16:19], v[44:47]
	v_mfma_f32_16x16x32_bf16 v[44:47], v[72:75], v[12:15], v[44:47]
	v_mfma_f32_16x16x32_bf16 v[44:47], v[68:71], v[92:95], v[44:47]
	v_mfma_f32_16x16x32_bf16 v[154:157], v[194:197], v[168:171], v[88:91]
	v_mfma_f32_16x16x32_bf16 v[88:91], v[60:63], v[20:23], v[44:47]
	s_waitcnt lgkmcnt(1)
	v_mfma_f32_16x16x32_bf16 v[44:47], v[158:161], v[142:145], v[52:55]
	s_waitcnt lgkmcnt(0)
	v_mfma_f32_16x16x32_bf16 v[44:47], v[172:175], v[134:137], v[44:47]
	s_nop 0
	v_cndmask_b32_e64 v52, 0, v108, s[12:13]
	s_waitcnt vmcnt(3)
	v_mfma_f32_16x16x32_bf16 v[16:19], v[36:39], v[16:19], v[44:47]
	s_waitcnt vmcnt(2)
	v_mfma_f32_16x16x32_bf16 v[12:15], v[32:35], v[12:15], v[16:19]
	s_nop 1
	v_cndmask_b32_e64 v44, v109, 0, s[14:15]
	v_cndmask_b32_e64 v45, 0, v110, s[16:17]
	v_cndmask_b32_e64 v46, 0, v111, s[20:21]
	v_mfma_f32_16x16x32_bf16 v[202:205], v[190:193], v[150:153], v[202:205]
	v_cndmask_b32_e64 v18, 0, v118, s[22:23]
	v_cndmask_b32_e64 v19, 0, v119, s[26:27]
	v_cndmask_b32_e64 v47, 0, v120, s[28:29]
	s_waitcnt vmcnt(1)
	v_mfma_f32_16x16x32_bf16 v[12:15], v[28:31], v[92:95], v[12:15]
	v_cndmask_b32_e64 v92, 0, v121, s[30:31]
	v_cvt_pk_bf16_f32 v16, v52, v44
	v_cvt_pk_bf16_f32 v17, v45, v46
	v_mfma_f32_16x16x32_bf16 v[202:205], v[194:197], v[104:107], v[202:205]
	v_cvt_pk_bf16_f32 v18, v18, v19
	v_cvt_pk_bf16_f32 v19, v47, v92
	s_movk_i32 s22, 0x1000
	s_waitcnt vmcnt(0)
	v_mfma_f32_16x16x32_bf16 v[52:55], v[24:27], v[20:23], v[12:15]
	v_mfma_f32_16x16x32_bf16 v[20:23], v[130:133], v[16:19], v[48:51]
	s_nop 1
	v_cvt_pk_bf16_f32 v12, v198, v199
	v_cvt_pk_bf16_f32 v13, v200, v201
	v_cvt_pk_bf16_f32 v14, v202, v203
	v_mfma_f32_16x16x32_bf16 v[16:19], v[158:161], v[16:19], v[64:67]
	v_cvt_pk_bf16_f32 v15, v204, v205
	s_nop 1
	v_mfma_f32_16x16x32_bf16 v[20:23], v[146:149], v[12:15], v[20:23]
	v_cndmask_b32_e64 v65, 0, v155, s[58:59]
	v_cndmask_b32_e64 v66, 0, v156, s[60:61]
	v_cndmask_b32_e64 v67, 0, v157, s[62:63]
	v_mfma_f32_16x16x32_bf16 v[12:15], v[172:175], v[12:15], v[16:19]
	v_mfma_f32_16x16x32_bf16 v[20:23], v[76:79], v[96:99], v[20:23]
	s_nop 1
	v_cndmask_b32_e32 v16, 0, v214, vcc
	v_cndmask_b32_e64 v17, 0, v215, s[34:35]
	v_mfma_f32_16x16x32_bf16 v[12:15], v[36:39], v[96:99], v[12:15]
	v_mfma_f32_16x16x32_bf16 v[244:247], v[190:193], v[236:239], v[244:247]
	v_mfma_f32_16x16x32_bf16 v[20:23], v[72:75], v[100:103], v[20:23]
	v_mfma_f32_16x16x32_bf16 v[12:15], v[32:35], v[100:103], v[12:15]
	v_mfma_f32_16x16x32_bf16 v[244:247], v[194:197], v[240:243], v[244:247]
	v_mfma_f32_16x16x32_bf16 v[20:23], v[68:71], v[150:153], v[20:23]
	v_mfma_f32_16x16x32_bf16 v[12:15], v[28:31], v[150:153], v[12:15]
	s_nop 5
	v_cndmask_b32_e64 v64, 0, v247, s[46:47]
	v_mfma_f32_16x16x32_bf16 v[48:51], v[60:63], v[104:107], v[20:23]
	s_nop 2
	v_cndmask_b32_e64 v20, 0, v216, s[36:37]
	v_cndmask_b32_e64 v21, 0, v217, s[38:39]
	v_cndmask_b32_e64 v22, 0, v244, s[40:41]
	v_cndmask_b32_e64 v23, 0, v245, s[42:43]
	v_mfma_f32_16x16x32_bf16 v[44:47], v[24:27], v[104:107], v[12:15]
	s_nop 2
	v_cvt_pk_bf16_f32 v12, v16, v17
	v_mfma_f32_16x16x32_bf16 v[16:19], v[130:133], v[40:43], v[56:59]
	v_cvt_pk_bf16_f32 v13, v20, v21
	v_cvt_pk_bf16_f32 v14, v22, v23
	v_cndmask_b32_e64 v15, 0, v246, s[44:45]
	v_mfma_f32_16x16x32_bf16 v[20:23], v[158:161], v[40:43], v[80:83]
	v_cvt_pk_bf16_f32 v15, v15, v64
	v_cndmask_b32_e64 v56, 0, v138, s[48:49]
	v_cndmask_b32_e64 v57, 0, v139, s[50:51]
	v_mfma_f32_16x16x32_bf16 v[16:19], v[146:149], v[12:15], v[16:19]
	v_cndmask_b32_e64 v58, 0, v140, s[52:53]
	v_cndmask_b32_e64 v59, 0, v141, s[54:55]
	v_cndmask_b32_e64 v64, 0, v154, s[56:57]
	v_mfma_f32_16x16x32_bf16 v[12:15], v[172:175], v[12:15], v[20:23]
	v_cvt_pk_bf16_f32 v56, v56, v57
	v_cvt_pk_bf16_f32 v57, v58, v59
	v_cvt_pk_bf16_f32 v58, v64, v65
	v_mfma_f32_16x16x32_bf16 v[12:15], v[36:39], v[206:209], v[12:15]
	v_cvt_pk_bf16_f32 v59, v66, v67
	v_mov_b64_e32 v[64:65], s[2:3]
	v_mad_i64_i32 v[64:65], s[4:5], v124, s96, v[64:65]
	v_mfma_f32_16x16x32_bf16 v[12:15], v[32:35], v[210:213], v[12:15]
	v_lshl_add_u64 v[64:65], v[64:65], 0, s[92:93]
	v_lshl_add_u64 v[64:65], v[126:127], 1, v[64:65]
	v_lshlrev_b32_e32 v66, 1, v128
	v_mfma_f32_16x16x32_bf16 v[12:15], v[28:31], v[236:239], v[12:15]
	v_mov_b32_e32 v67, v177
	v_lshl_add_u64 v[64:65], v[64:65], 0, v[66:67]
	s_mov_b64 s[4:5], 0x1000
	v_mfma_f32_16x16x32_bf16 v[20:23], v[24:27], v[240:243], v[12:15]
	v_lshl_add_u64 v[66:67], v[64:65], 0, s[4:5]
	s_mov_b32 s4, 0x2b000
	v_mfma_f32_16x16x32_bf16 v[12:15], v[130:133], v[40:43], v[84:87]
	v_mfma_f32_16x16x32_bf16 v[12:15], v[146:149], v[56:59], v[12:15]
	v_mfma_f32_16x16x32_bf16 v[16:19], v[76:79], v[206:209], v[16:19]
	v_mfma_f32_16x16x32_bf16 v[12:15], v[76:79], v[248:251], v[12:15]
	v_mfma_f32_16x16x32_bf16 v[16:19], v[72:75], v[210:213], v[16:19]
	v_mfma_f32_16x16x32_bf16 v[12:15], v[72:75], v[228:231], v[12:15]
	v_mfma_f32_16x16x32_bf16 v[8:11], v[158:161], v[40:43], v[8:11]
	global_load_dwordx2 v[40:41], v[66:67], off offset:32
	v_mfma_f32_16x16x32_bf16 v[16:19], v[68:71], v[236:239], v[16:19]
	v_mfma_f32_16x16x32_bf16 v[12:15], v[68:71], v[114:117], v[12:15]
	v_mfma_f32_16x16x32_bf16 v[8:11], v[172:175], v[56:59], v[8:11]
	v_mfma_f32_16x16x32_bf16 v[16:19], v[60:63], v[240:243], v[16:19]
	v_mfma_f32_16x16x32_bf16 v[12:15], v[60:63], v[168:171], v[12:15]
	v_add_co_u32_e32 v60, vcc, s22, v64
	v_mfma_f32_16x16x32_bf16 v[8:11], v[36:39], v[248:251], v[8:11]
	s_nop 0
	v_addc_co_u32_e32 v61, vcc, 0, v65, vcc
	v_add_co_u32_e32 v62, vcc, s4, v64
	s_mov_b32 s4, 0x55000
	s_nop 0
	v_addc_co_u32_e32 v63, vcc, 0, v65, vcc
	v_add_co_u32_e32 v56, vcc, s4, v64
	v_mfma_f32_16x16x32_bf16 v[8:11], v[32:35], v[228:231], v[8:11]
	s_nop 0
	v_addc_co_u32_e32 v57, vcc, 0, v65, vcc
	s_mov_b32 s4, 0x7f000
	v_add_co_u32_e32 v58, vcc, s4, v64
	global_load_dwordx2 v[42:43], v[60:61], off
	global_load_dwordx2 v[38:39], v[62:63], off
	global_load_dwordx2 v[34:35], v[56:57], off
	global_load_dwordx2 v[36:37], v[62:63], off offset:32
	v_addc_co_u32_e32 v59, vcc, 0, v65, vcc
	v_mfma_f32_16x16x32_bf16 v[8:11], v[28:31], v[114:117], v[8:11]
	global_load_dwordx2 v[30:31], v[58:59], off
	global_load_dwordx2 v[28:29], v[58:59], off offset:32
	global_load_dwordx2 v[32:33], v[56:57], off offset:32
	v_mul_f32_e32 v56, v91, v91
	v_fmac_f32_e32 v56, v90, v90
	v_mfma_f32_16x16x32_bf16 v[8:11], v[24:27], v[168:171], v[8:11]
	v_mul_f32_e32 v27, v89, v89
	v_and_b32_e32 v25, 64, v225
	v_fmac_f32_e32 v27, v88, v88
	v_xor_b32_e32 v24, 16, v225
	v_add_u32_e32 v25, 64, v25
	v_add_f32_e32 v27, v27, v56
	v_mul_f32_e32 v56, v53, v53
	v_mul_f32_e32 v57, v55, v55
	v_cmp_lt_i32_e32 vcc, v24, v25
	v_fmac_f32_e32 v56, v52, v52
	v_fmac_f32_e32 v57, v54, v54
	v_cndmask_b32_e32 v24, v225, v24, vcc
	v_add_f32_e32 v56, v56, v57
	v_lshlrev_b32_e32 v24, 2, v24
	v_add_f32_e32 v27, v27, v56
	ds_bpermute_b32 v56, v24, v27
	v_xor_b32_e32 v26, 32, v225
	v_cmp_lt_i32_e32 vcc, v26, v25
	v_lshlrev_b32_e32 v57, 2, v129
	s_waitcnt lgkmcnt(0)
	v_add_f32_e32 v27, v27, v56
	v_cndmask_b32_e32 v25, v225, v26, vcc
	v_lshlrev_b32_e32 v26, 2, v25
	ds_bpermute_b32 v56, v26, v27
	v_and_b32_e32 v25, 0x3fffffc0, v125
	v_lshlrev_b32_e32 v25, 2, v25
	v_cmp_eq_u32_e32 vcc, 0, v164
	v_add3_u32 v25, 0, v25, v57
	s_and_saveexec_b64 s[4:5], vcc
	s_cbranch_execz .LBB0_100
	s_waitcnt lgkmcnt(0)
	v_add_f32_e32 v27, v27, v56
	ds_write_b32 v25, v27

.LBB0_129:
	v_add_u32_e32 v5, s7, v2
	v_add_u32_e32 v4, -7, v1
	v_add_u32_e32 v6, 31, v5
	v_cndmask_b32_e32 v4, v6, v4, vcc
	v_lshl_add_u32 v140, v4, 9, v0
	v_add_u32_e32 v4, -6, v1
	v_add_u32_e32 v6, 30, v5
	v_cndmask_b32_e32 v4, v6, v4, vcc
	v_lshl_add_u32 v141, v4, 9, v0
	v_add_u32_e32 v4, -5, v1
	v_add_u32_e32 v6, 29, v5
	v_cndmask_b32_e32 v4, v6, v4, vcc
	v_lshl_add_u32 v142, v4, 9, v0
	v_add_u32_e32 v4, -4, v1
	v_add_u32_e32 v6, 28, v5
	v_cndmask_b32_e32 v4, v6, v4, vcc
	v_lshl_add_u32 v143, v4, 9, v0
	v_add_u32_e32 v4, -3, v1
	v_add_u32_e32 v6, 27, v5
	v_cndmask_b32_e32 v4, v6, v4, vcc
	v_lshl_add_u32 v144, v4, 9, v0
	v_add_u32_e32 v4, -2, v1
	v_add_u32_e32 v6, 26, v5
	v_cndmask_b32_e32 v4, v6, v4, vcc
	v_lshl_add_u32 v145, v4, 9, v0
	v_add_u32_e32 v4, -1, v1
	v_add_u32_e32 v6, 25, v5
	v_cndmask_b32_e32 v4, v6, v4, vcc
	v_lshl_add_u32 v146, v4, 9, v0
	v_add_u32_e32 v4, 24, v5
	v_cndmask_b32_e32 v4, v4, v1, vcc
	v_lshl_add_u32 v147, v4, 9, v0
	ds_read_b32 v148, v140
	ds_read_b32 v149, v141
	ds_read_b32 v150, v142
	ds_read_b32 v151, v143
	ds_read_b32 v152, v144
	ds_read_b32 v153, v145
	ds_read_b32 v154, v146
	ds_read_b32 v155, v147
	s_add_i32 s7, s7, -8
	s_cmp_eq_u32 s7, 0
	v_add_u32_e32 v1, 8, v1
	s_waitcnt lgkmcnt(7)
	v_add_f32_e32 v3, v3, v148
	ds_write_b32 v140, v3
	s_waitcnt lgkmcnt(7)
	v_add_f32_e32 v3, v3, v149
	ds_write_b32 v141, v3
	s_waitcnt lgkmcnt(7)
	v_add_f32_e32 v3, v3, v150
	ds_write_b32 v142, v3
	s_waitcnt lgkmcnt(7)
	v_add_f32_e32 v3, v3, v151
	ds_write_b32 v143, v3
	s_waitcnt lgkmcnt(7)
	v_add_f32_e32 v3, v3, v152
	ds_write_b32 v144, v3
	s_waitcnt lgkmcnt(7)
	v_add_f32_e32 v3, v3, v153
	ds_write_b32 v145, v3
	s_waitcnt lgkmcnt(7)
	v_add_f32_e32 v3, v3, v154
	ds_write_b32 v146, v3
	s_waitcnt lgkmcnt(7)
	v_add_f32_e32 v3, v3, v155
	ds_write_b32 v147, v3
	s_cbranch_scc0 .LBB0_129
	v_lshlrev_b32_e32 v2, 2, v40
	v_add_u32_e32 v3, 0, v2
	v_lshl_add_u32 v4, v77, 9, v3
	s_waitcnt lgkmcnt(0)
	s_barrier
	ds_read2st64_b32 v[0:1], v3 offset0:94 offset1:224
	ds_read_b32 v5, v4 offset:8192
	v_lshlrev_b32_e32 v22, 7, v77
	v_lshlrev_b32_e32 v23, 7, v76
	v_sub_u32_e32 v6, v40, v23
	v_lshl_add_u32 v6, v6, 2, 0
	s_waitcnt lgkmcnt(0)
	v_add_f32_e32 v5, v0, v5
	ds_write_b32 v4, v5 offset:8192
	v_sub_u32_e32 v4, v40, v22
	v_lshl_add_u32 v4, v4, 2, 0
	v_add_u32_e32 v4, 0x11e00, v4
	ds_read_b32 v5, v4
	v_lshlrev_b32_e32 v24, 7, v75
	v_lshlrev_b32_e32 v25, 7, v74
	v_lshlrev_b32_e32 v26, 7, v73
	v_lshlrev_b32_e32 v27, 7, v72
	s_waitcnt lgkmcnt(0)
	v_add_f32_e32 v5, v1, v5
	ds_write_b32 v4, v5
	v_lshl_add_u32 v4, v76, 9, v3
	ds_read_b32 v5, v4 offset:8192
	v_lshlrev_b32_e32 v28, 7, v71
	v_lshlrev_b32_e32 v29, 7, v70
	v_sub_u32_e32 v8, v40, v29
	v_lshl_add_u32 v8, v8, 2, 0
	s_waitcnt lgkmcnt(0)
	v_add_f32_e32 v5, v0, v5
	ds_write_b32 v4, v5 offset:8192
	v_add_u32_e32 v4, 0x11e00, v6
	ds_read_b32 v5, v4
	v_lshl_add_u32 v6, v75, 9, v3
	v_add_u32_e32 v8, 0x11e00, v8
	v_lshl_or_b32 v9, v67, 9, v2
	v_lshl_or_b32 v10, v66, 9, v2
	s_waitcnt lgkmcnt(0)
	v_add_f32_e32 v5, v1, v5
	ds_write_b32 v4, v5
	ds_read_b32 v4, v6 offset:8192
	v_sub_u32_e32 v5, v40, v24
	v_lshl_add_u32 v5, v5, 2, 0
	v_add_u32_e32 v5, 0x11e00, v5
	v_mul_u32_u24_e32 v12, 0x48, v40
	s_waitcnt lgkmcnt(0)
	v_add_f32_e32 v4, v0, v4
	ds_write_b32 v6, v4 offset:8192
	ds_read_b32 v4, v5
	v_lshl_add_u32 v6, v74, 9, v3
	s_waitcnt vmcnt(9)
	v_lshlrev_b32_e32 v15, 16, v62
	v_lshlrev_b32_e32 v14, 16, v61
	s_waitcnt vmcnt(6)
	v_lshlrev_b32_e32 v19, 16, v56
	s_waitcnt lgkmcnt(0)
	v_add_f32_e32 v4, v1, v4
	ds_write_b32 v5, v4
	ds_read_b32 v4, v6 offset:8192
	v_sub_u32_e32 v5, v40, v25
	v_lshl_add_u32 v5, v5, 2, 0
	v_add_u32_e32 v5, 0x11e00, v5
	v_lshlrev_b32_e32 v18, 16, v55
	s_waitcnt lgkmcnt(0)
	v_add_f32_e32 v4, v0, v4
	ds_write_b32 v6, v4 offset:8192
	ds_read_b32 v4, v5
	v_lshl_add_u32 v6, v73, 9, v3
	v_readlane_b32 s4, v255, 8
	s_waitcnt lgkmcnt(0)
	v_add_f32_e32 v4, v1, v4
	ds_write_b32 v5, v4
	ds_read_b32 v4, v6 offset:8192
	v_sub_u32_e32 v5, v40, v26
	v_lshl_add_u32 v5, v5, 2, 0
	v_add_u32_e32 v5, 0x11e00, v5
	s_waitcnt lgkmcnt(0)
	v_add_f32_e32 v4, v0, v4
	ds_write_b32 v6, v4 offset:8192
	ds_read_b32 v4, v5
	v_lshl_add_u32 v6, v72, 9, v3
	s_waitcnt lgkmcnt(0)
	v_add_f32_e32 v4, v1, v4
	ds_write_b32 v5, v4
	ds_read_b32 v4, v6 offset:8192
	v_sub_u32_e32 v5, v40, v27
	v_lshl_add_u32 v5, v5, 2, 0
	v_add_u32_e32 v5, 0x11e00, v5
	s_waitcnt lgkmcnt(0)
	v_add_f32_e32 v4, v0, v4
	ds_write_b32 v6, v4 offset:8192
	ds_read_b32 v4, v5
	v_lshl_add_u32 v6, v71, 9, v3
	s_waitcnt lgkmcnt(0)
	v_add_f32_e32 v4, v1, v4
	ds_write_b32 v5, v4
	ds_read_b32 v4, v6 offset:8192
	v_sub_u32_e32 v5, v40, v28
	v_lshl_add_u32 v5, v5, 2, 0
	v_add_u32_e32 v7, 0x11e00, v5
	v_lshlrev_b32_e32 v5, 16, v69
	s_waitcnt lgkmcnt(0)
	v_add_f32_e32 v4, v0, v4
	ds_write_b32 v6, v4 offset:8192
	ds_read_b32 v4, v7
	v_lshl_add_u32 v6, v70, 9, v3
	s_waitcnt lgkmcnt(0)
	v_add_f32_e32 v4, v1, v4
	ds_write_b32 v7, v4
	ds_read_b32 v7, v6 offset:8192
	v_lshlrev_b32_e32 v4, 16, v68
	s_waitcnt lgkmcnt(0)
	v_add_f32_e32 v0, v0, v7
	ds_write_b32 v6, v0 offset:8192
	ds_read_b32 v0, v8
	v_lshl_or_b32 v6, v60, 12, v2
	v_add_u32_e32 v6, 0, v6
	s_waitcnt lgkmcnt(0)
	v_add_f32_e32 v0, v1, v0
	ds_write_b32 v8, v0
	s_waitcnt lgkmcnt(0)
	s_barrier
	ds_read2st64_b32 v[0:1], v3 offset0:158 offset1:160
	ds_read2st64_b32 v[6:7], v6 offset0:32 offset1:160
	v_add_u32_e32 v3, 0, v9
	ds_read2st64_b32 v[8:9], v3 offset0:32 offset1:160
	v_add_u32_e32 v3, 0, v10
	ds_read2st64_b32 v[10:11], v3 offset0:32 offset1:160
	s_waitcnt lgkmcnt(2)
	v_sub_f32_e32 v3, v0, v6
	v_sub_f32_e32 v6, v1, v7
	s_waitcnt lgkmcnt(1)
	v_sub_f32_e32 v7, v0, v8
	v_sub_f32_e32 v8, v1, v9
	v_mul_f32_e32 v3, 0x3fb8aa3b, v3
	v_mul_f32_e32 v9, 0x3fb8aa3b, v6
	v_mul_f32_e32 v7, 0x3fb8aa3b, v7
	v_mul_f32_e32 v13, 0x3fb8aa3b, v8
	v_exp_f32_e32 v6, v3
	v_exp_f32_e32 v8, v9
	v_exp_f32_e32 v7, v7
	v_exp_f32_e32 v9, v13
	s_waitcnt lgkmcnt(0)
	v_sub_f32_e32 v11, v1, v11
	v_mul_f32_e32 v11, 0x3fb8aa3b, v11
	v_pk_mul_f32 v[6:7], v[6:7], v[4:5]
	v_pk_mul_f32 v[8:9], v[8:9], v[4:5]
	v_lshl_or_b32 v4, v65, 9, v2
	v_add_u32_e32 v4, 0, v4
	ds_read2st64_b32 v[4:5], v4 offset0:32 offset1:160
	v_lshlrev_b32_e32 v3, 1, v12
	v_sub_f32_e32 v10, v0, v10
	v_exp_f32_e32 v12, v11
	v_mul_f32_e32 v10, 0x3fb8aa3b, v10
	s_waitcnt lgkmcnt(0)
	v_sub_f32_e32 v4, v0, v4
	v_mul_f32_e32 v4, 0x3fb8aa3b, v4
	v_exp_f32_e32 v11, v4
	v_sub_f32_e32 v4, v1, v5
	v_mul_f32_e32 v4, 0x3fb8aa3b, v4
	v_exp_f32_e32 v10, v10
	v_exp_f32_e32 v13, v4
	v_lshl_or_b32 v4, v64, 9, v2
	v_add_u32_e32 v4, 0, v4
	ds_read2st64_b32 v[4:5], v4 offset0:32 offset1:160
	v_pk_mul_f32 v[10:11], v[10:11], v[14:15]
	v_pk_mul_f32 v[12:13], v[12:13], v[14:15]
	v_lshl_or_b32 v14, v63, 9, v2
	v_add_u32_e32 v14, 0, v14
	ds_read2st64_b32 v[14:15], v14 offset0:32 offset1:160
	s_waitcnt lgkmcnt(1)
	v_sub_f32_e32 v5, v1, v5
	v_mul_f32_e32 v5, 0x3fb8aa3b, v5
	v_exp_f32_e32 v16, v5
	v_sub_f32_e32 v4, v0, v4
	s_waitcnt lgkmcnt(0)
	v_sub_f32_e32 v5, v0, v14
	v_sub_f32_e32 v14, v1, v15
	v_mul_f32_e32 v14, 0x3fb8aa3b, v14
	v_exp_f32_e32 v17, v14
	v_lshl_or_b32 v14, v59, 9, v2
	v_add_u32_e32 v14, 0, v14
	v_mul_f32_e32 v4, 0x3fb8aa3b, v4
	v_mul_f32_e32 v5, 0x3fb8aa3b, v5
	ds_read2st64_b32 v[14:15], v14 offset0:32 offset1:160
	v_exp_f32_e32 v4, v4
	v_exp_f32_e32 v5, v5
	v_pk_mul_f32 v[16:17], v[16:17], v[18:19]
	s_waitcnt lgkmcnt(0)
	v_sub_f32_e32 v15, v1, v15
	v_pk_mul_f32 v[20:21], v[4:5], v[18:19]
	v_sub_f32_e32 v4, v0, v14
	v_mul_f32_e32 v14, 0x3fb8aa3b, v4
	v_lshl_or_b32 v4, v57, 9, v2
	v_add_u32_e32 v4, 0, v4
	ds_read2st64_b32 v[4:5], v4 offset0:32 offset1:160
	v_mul_f32_e32 v15, 0x3fb8aa3b, v15
	v_exp_f32_e32 v18, v15
	v_exp_f32_e32 v14, v14
	s_waitcnt lgkmcnt(0)
	v_sub_f32_e32 v4, v0, v4
	v_mul_f32_e32 v4, 0x3fb8aa3b, v4
	v_exp_f32_e32 v15, v4
	v_sub_f32_e32 v4, v1, v5
	v_mul_f32_e32 v4, 0x3fb8aa3b, v4
	v_exp_f32_e32 v19, v4
	s_waitcnt vmcnt(4)
	v_lshlrev_b32_e32 v5, 16, v58
	v_lshlrev_b32_e32 v4, 16, v54
	v_pk_mul_f32 v[14:15], v[14:15], v[4:5]
	v_pk_mul_f32 v[18:19], v[18:19], v[4:5]
	v_cvt_pk_bf16_f32 v5, v10, v11
	v_lshlrev_b32_e32 v10, 1, v50
	v_cvt_pk_bf16_f32 v4, v6, v7
	v_cvt_pk_bf16_f32 v6, v20, v21
	v_cvt_pk_bf16_f32 v7, v14, v15
	v_add3_u32 v30, s4, v3, v10
	ds_write_b128 v30, v[4:7]
	v_cvt_pk_bf16_f32 v4, v8, v9
	v_cvt_pk_bf16_f32 v5, v12, v13
	v_cvt_pk_bf16_f32 v6, v16, v17
	v_cvt_pk_bf16_f32 v7, v18, v19
	v_add3_u32 v3, s29, v3, v10
	ds_write_b128 v3, v[4:7]
	v_or_b32_e32 v4, v22, v40
	v_lshl_add_u32 v4, v4, 2, 0
	ds_read2st64_b32 v[4:5], v4 offset0:32 offset1:160
	v_or_b32_e32 v6, v23, v40
	v_lshl_add_u32 v6, v6, 2, 0
	ds_read2st64_b32 v[6:7], v6 offset0:32 offset1:160
	s_waitcnt vmcnt(2)
	v_lshlrev_b32_e32 v11, 16, v53
	s_waitcnt lgkmcnt(1)
	v_sub_f32_e32 v5, v1, v5
	v_mul_f32_e32 v5, 0x3fb8aa3b, v5
	v_sub_f32_e32 v4, v0, v4
	v_exp_f32_e32 v8, v5
	s_waitcnt lgkmcnt(0)
	v_sub_f32_e32 v5, v0, v6
	v_sub_f32_e32 v6, v1, v7
	v_mul_f32_e32 v4, 0x3fb8aa3b, v4
	v_mul_f32_e32 v5, 0x3fb8aa3b, v5
	v_mul_f32_e32 v6, 0x3fb8aa3b, v6
	v_exp_f32_e32 v4, v4
	v_exp_f32_e32 v5, v5
	v_exp_f32_e32 v9, v6
	v_or_b32_e32 v6, v24, v40
	v_lshl_add_u32 v6, v6, 2, 0
	v_lshlrev_b32_e32 v10, 16, v52
	ds_read2st64_b32 v[6:7], v6 offset0:32 offset1:160
	v_pk_mul_f32 v[4:5], v[4:5], v[10:11]
	v_pk_mul_f32 v[8:9], v[8:9], v[10:11]
	v_or_b32_e32 v10, v25, v40
	v_lshl_add_u32 v10, v10, 2, 0
	ds_read2st64_b32 v[10:11], v10 offset0:32 offset1:160
	s_waitcnt lgkmcnt(1)
	v_sub_f32_e32 v7, v1, v7
	v_mul_f32_e32 v7, 0x3fb8aa3b, v7
	v_sub_f32_e32 v6, v0, v6
	v_exp_f32_e32 v12, v7
	s_waitcnt lgkmcnt(0)
	v_sub_f32_e32 v7, v0, v10
	v_sub_f32_e32 v10, v1, v11
	v_mul_f32_e32 v6, 0x3fb8aa3b, v6
	v_mul_f32_e32 v7, 0x3fb8aa3b, v7
	v_mul_f32_e32 v10, 0x3fb8aa3b, v10
	v_exp_f32_e32 v6, v6
	v_exp_f32_e32 v7, v7
	v_exp_f32_e32 v13, v10
	v_or_b32_e32 v10, v26, v40
	v_lshl_add_u32 v10, v10, 2, 0
	v_lshlrev_b32_e32 v15, 16, v51
	s_waitcnt vmcnt(1)
	v_lshlrev_b32_e32 v14, 16, v49
	ds_read2st64_b32 v[10:11], v10 offset0:32 offset1:160
	v_pk_mul_f32 v[6:7], v[6:7], v[14:15]
	v_pk_mul_f32 v[12:13], v[12:13], v[14:15]
	v_or_b32_e32 v14, v27, v40
	v_lshl_add_u32 v14, v14, 2, 0
	ds_read2st64_b32 v[14:15], v14 offset0:32 offset1:160
	s_waitcnt lgkmcnt(1)
	v_sub_f32_e32 v11, v1, v11
	v_mul_f32_e32 v11, 0x3fb8aa3b, v11
	v_sub_f32_e32 v10, v0, v10
	v_exp_f32_e32 v16, v11
	s_waitcnt lgkmcnt(0)
	v_sub_f32_e32 v11, v0, v14
	v_sub_f32_e32 v14, v1, v15
	v_mul_f32_e32 v10, 0x3fb8aa3b, v10
	v_mul_f32_e32 v11, 0x3fb8aa3b, v11
	v_mul_f32_e32 v14, 0x3fb8aa3b, v14
	v_exp_f32_e32 v10, v10
	v_exp_f32_e32 v11, v11
	v_exp_f32_e32 v17, v14
	v_or_b32_e32 v14, v28, v40
	v_lshl_add_u32 v14, v14, 2, 0
	v_lshlrev_b32_e32 v19, 16, v47
	v_lshlrev_b32_e32 v18, 16, v43
	ds_read2st64_b32 v[14:15], v14 offset0:32 offset1:160
	v_pk_mul_f32 v[10:11], v[10:11], v[18:19]
	v_pk_mul_f32 v[16:17], v[16:17], v[18:19]
	v_or_b32_e32 v18, v29, v40
	v_lshl_add_u32 v18, v18, 2, 0
	ds_read2st64_b32 v[18:19], v18 offset0:32 offset1:160
	s_waitcnt lgkmcnt(1)
	v_sub_f32_e32 v15, v1, v15
	v_mul_f32_e32 v15, 0x3fb8aa3b, v15
	v_sub_f32_e32 v14, v0, v14
	v_exp_f32_e32 v20, v15
	s_waitcnt lgkmcnt(0)
	v_sub_f32_e32 v15, v0, v18
	v_mul_f32_e32 v14, 0x3fb8aa3b, v14
	v_mul_f32_e32 v15, 0x3fb8aa3b, v15
	v_sub_f32_e32 v18, v1, v19
	v_exp_f32_e32 v14, v14
	v_exp_f32_e32 v15, v15
	v_mul_f32_e32 v18, 0x3fb8aa3b, v18
	v_exp_f32_e32 v21, v18
	s_waitcnt vmcnt(0)
	v_lshlrev_b32_e32 v19, 16, v48
	v_lshlrev_b32_e32 v18, 16, v41
	v_pk_mul_f32 v[14:15], v[14:15], v[18:19]
	v_pk_mul_f32 v[18:19], v[20:21], v[18:19]
	v_cvt_pk_bf16_f32 v4, v4, v5
	v_cvt_pk_bf16_f32 v5, v6, v7
	v_cvt_pk_bf16_f32 v6, v10, v11
	v_cvt_pk_bf16_f32 v7, v14, v15
	s_movk_i32 s4, 0x7f
	ds_write_b128 v30, v[4:7] offset:64
	v_cvt_pk_bf16_f32 v4, v8, v9
	v_cvt_pk_bf16_f32 v5, v12, v13
	v_cvt_pk_bf16_f32 v6, v16, v17
	v_cvt_pk_bf16_f32 v7, v18, v19
	v_cmp_lt_i32_e32 vcc, s4, v46
	ds_write_b128 v3, v[4:7] offset:64
	s_and_saveexec_b64 s[4:5], vcc
	s_xor_b64 s[4:5], exec, s[4:5]
	s_ashr_i32 s7, s6, 31
	s_or_saveexec_b64 s[4:5], s[4:5]
	v_mov_b64_e32 v[16:17], s[6:7]
	s_xor_b64 exec, exec, s[4:5]
	s_cbranch_execz .LBB0_127
	v_mul_f32_e32 v0, 0x3fb8aa3b, v0
	v_exp_f32_e32 v0, v0
	s_ashr_i32 s7, s6, 31
	v_mul_f32_e32 v1, 0x3fb8aa3b, v1
	s_lshl_b64 s[10:11], s[6:7], 10
	v_exp_f32_e32 v1, v1
	v_readlane_b32 s12, v253, 16
	v_readlane_b32 s13, v253, 17
	s_add_u32 s10, s12, s10
	s_addc_u32 s11, s13, s11
	v_mov_b64_e32 v[16:17], s[6:7]
	global_store_dword v2, v0, s[10:11]
	global_store_dword v2, v1, s[10:11] offset:512
	s_branch .LBB0_127
